# combo12 + P4 set-up: rel_bias table load issued with the gain loads (one round trip instead of two)
# speedup vs baseline: 1.0025x; 1.0025x over previous
.LBB0_1601:
	s_cmp_lt_i32 s72, 5
	s_cselect_b64 s[4:5], -1, 0
	s_add_u32 s6, s70, 0x21900000
	s_addc_u32 s7, s71, 0
	s_and_b64 s[4:5], s[4:5], s[0:1]
	s_andn2_b64 vcc, exec, s[4:5]
	s_cbranch_vccnz .LBB0_1667
	v_mov_b32_e32 v253, 0
	v_mov_b32_e32 v6, s60
	v_mov_b32_e32 v7, s61
	v_lshl_add_u64 v[6:7], v[252:253], 2, v[6:7]
	global_load_dword v8, v[6:7], off
	s_movk_i32 s0, 0x7f
	v_cmp_lt_u32_e32 vcc, s0, v252
	s_and_saveexec_b64 s[0:1], vcc
	s_xor_b64 s[0:1], exec, s[0:1]
	v_mov_b32_e32 v253, 0
	s_andn2_saveexec_b64 s[8:9], s[0:1]
	s_cbranch_execz .LBB0_1608
	v_cmp_lt_u32_e32 vcc, 15, v252
	v_mov_b32_e32 v0, v252
	s_and_saveexec_b64 s[10:11], vcc
	s_cbranch_execz .LBB0_1607
	v_cvt_f32_u32_e32 v0, v252
	s_mov_b32 s0, 0x800000
	s_mov_b32 s1, 0x7f800000
	s_mov_b32 s3, 0x40051592
	v_mul_f32_e32 v0, 0x3d800000, v0
	v_cmp_gt_f32_e32 vcc, s0, v0
	s_mov_b32 s0, 0x3f317217
	s_nop 0
	v_cndmask_b32_e64 v1, 0, 32, vcc
	v_ldexp_f32 v0, v0, v1
	v_log_f32_e32 v0, v0
	v_mov_b32_e32 v1, 0x41b17218
	v_cndmask_b32_e32 v1, 0, v1, vcc
	v_mul_f32_e32 v2, 0x3f317217, v0
	v_fma_f32 v2, v0, s0, -v2
	v_fmamk_f32 v2, v0, 0x3377d1cf, v2
	v_fmac_f32_e32 v2, 0x3f317217, v0
	v_cmp_lt_f32_e64 s[0:1], |v0|, s1
	s_nop 1
	v_cndmask_b32_e64 v0, v0, v2, s[0:1]
	v_sub_f32_e32 v0, v0, v1
	v_div_scale_f32 v1, s[0:1], s3, s3, v0
	v_rcp_f32_e32 v2, v1
	s_nop 0
	v_fma_f32 v3, -v1, v2, 1.0
	v_fmac_f32_e32 v2, v3, v2
	v_div_scale_f32 v3, vcc, v0, s3, v0
	v_mul_f32_e32 v4, v3, v2
	v_fma_f32 v5, -v1, v4, v3
	v_fmac_f32_e32 v4, v5, v2
	v_fma_f32 v1, -v1, v4, v3
	v_div_fmas_f32 v1, v1, v2, v4
	v_div_fixup_f32 v0, v1, s3, v0
	v_mul_f32_e32 v0, 0x41800000, v0
	v_cvt_i32_f32_e32 v0, v0
	v_min_i32_e32 v0, 15, v0
	v_add_u32_e32 v0, 16, v0

.LBB0_1608:
	s_or_b64 exec, exec, s[8:9]
	v_lshl_add_u32 v1, v252, 2, 0
	v_add_u32_e32 v1, 0x15a00, v1
	s_cmpk_gt_i32 s2, 0xff
	s_waitcnt vmcnt(0)
	ds_write_b32 v1, v8
	s_cbranch_scc1 .LBB0_1667
	v_readlane_b32 s12, v255, 5
	v_lshlrev_b32_e32 v0, 3, v252
	v_lshlrev_b32_e32 v1, 4, v252
	v_lshlrev_b32_e32 v3, 1, v252
	s_lshl_b32 s0, s12, 7
	v_and_b32_e32 v2, 0xc0, v1
	v_and_b32_e32 v3, 32, v3
	v_and_b32_e32 v4, 0x118, v0
	s_add_i32 s3, s0, 0
	v_or3_b32 v2, v3, v2, v4
	v_or_b32_e32 v3, s0, v222
	s_ashr_i32 s0, s0, 4
	s_and_b32 s8, s0, -16
	s_lshr_b32 s0, s0, 1
	v_readlane_b32 s11, v255, 1
	s_add_i32 s3, s3, 0x14200
	s_and_b32 s0, s0, 4
	s_bfe_u32 s17, s11, 0x20006
	s_add_u32 s18, s70, 0x21a00000
	s_addc_u32 s19, s71, 0
	s_add_u32 s33, s70, 0x13b00000
	v_lshrrev_b32_e32 v5, 1, v252
	s_addc_u32 s34, s71, 0
	v_bfe_u32 v4, v252, 2, 2
	v_and_b32_e32 v5, 8, v5
	s_add_u32 s35, s70, 0x16300000
	v_or3_b32 v6, v5, v4, s8
	v_and_b32_e32 v7, 15, v252
	v_ashrrev_i32_e32 v9, 4, v3
	s_addc_u32 s38, s71, 0
	v_or_b32_e32 v6, s0, v6
	v_bitop3_b32 v10, v9, v7, 3 bitop3:0x6c
	v_lshlrev_b32_e32 v9, 9, v9
	s_movk_i32 s9, 0x60
	s_add_u32 s39, s70, 0x16b00000
	v_and_b32_e32 v0, 24, v0
	v_lshlrev_b32_e32 v6, 9, v6
	v_and_b32_e32 v8, 32, v252
	v_lshl_or_b32 v132, v10, 3, v9
	v_or_b32_e32 v9, 64, v3
	v_bitop3_b32 v3, v3, s9, 64 bitop3:0xc8
	s_addc_u32 s44, s71, 0
	s_lshr_b32 s10, s11, 3
	v_or3_b32 v130, v0, v8, v6
	v_or3_b32 v134, v0, v3, v6
	v_ashrrev_i32_e32 v6, 4, v9
	v_and_b32_e32 v167, 31, v252
	s_and_b32 s45, s10, 0x1fffffe0
	v_bitop3_b32 v7, v6, v7, 7 bitop3:0x6c
	v_lshlrev_b32_e32 v6, 9, v6
	v_or_b32_e32 v169, s45, v167
	s_movk_i32 s50, 0x108
	v_lshrrev_b32_e32 v166, 5, v222
	v_lshl_or_b32 v136, v7, 3, v6
	v_mul_lo_u32 v6, v169, s50
	s_add_i32 s51, 0, 0x10000
	s_movk_i32 s1, 0xc0
	v_add_u32_e32 v170, s51, v6
	v_lshlrev_b32_e32 v6, 4, v166
	v_and_b32_e32 v7, 0x70, v1
	v_bitop3_b32 v178, v6, v7, s1 bitop3:0x36
	s_movk_i32 s1, 0xe0
	v_bitop3_b32 v179, v6, v7, s1 bitop3:0x36
	s_add_i32 s1, 0, 0x4000
	v_bitop3_b32 v175, v6, v7, s9 bitop3:0x36
	s_movk_i32 s9, 0x80
	v_add_u32_e32 v181, s1, v2
	s_lshl_b32 s1, s12, 13
	v_bitop3_b32 v176, v6, v7, s9 bitop3:0x36
	s_movk_i32 s9, 0xa0
	s_add_i32 s56, s1, 0
	s_lshr_b32 s1, s11, 8
	v_bitop3_b32 v177, v6, v7, s9 bitop3:0x36
	s_lshl_b32 s54, s17, 10
	s_lshl_b32 s9, s1, 7
	s_movk_i32 s10, 0x70
	s_add_i32 s9, s54, s9
	v_bitop3_b32 v172, v6, v1, s10 bitop3:0x78
	v_lshl_or_b32 v1, v167, 2, s9
	v_sub_u32_e32 v183, v1, v6
	v_or_b32_e32 v1, s8, v5
	v_or3_b32 v1, v1, s0, v4
	v_lshlrev_b32_e32 v1, 9, v1
	v_mov_b32_e32 v139, 0
	v_or3_b32 v138, v1, v8, v0
	s_mul_i32 s0, s1, 0x2100
	s_lshl_b32 s20, s12, 11
	v_lshlrev_b32_e32 v180, 2, v166
	s_add_i32 s55, s54, 0
	v_mov_b32_e32 v133, v139
	v_mov_b32_e32 v137, v139
	v_lshlrev_b64 v[144:145], 1, v[138:139]
	v_or3_b32 v138, v1, v3, v0
	v_mov_b32_e32 v0, s0
	v_add_u32_e32 v168, 0, v2
	v_lshl_add_u32 v171, v167, 8, 0
	v_bitop3_b32 v173, v6, v7, 32 bitop3:0x36
	v_bitop3_b32 v174, v6, v7, 64 bitop3:0x36
	s_add_i32 s55, s55, 0x14600
	v_mov_b32_e32 v131, v139
	v_mov_b32_e32 v135, v139
	v_sub_u32_e32 v182, v169, v180
	v_lshlrev_b64 v[140:141], 1, v[132:133]
	v_lshlrev_b64 v[142:143], 1, v[136:137]
	v_lshlrev_b64 v[146:147], 1, v[138:139]
	v_mad_u32_u24 v184, v167, s50, v0
	s_movk_i32 s57, 0x400
	s_movk_i32 s58, 0x71
	s_add_i32 s59, 0, 0x15600
	s_movk_i32 s60, 0x1ff
	v_mov_b32_e32 v185, 0x358637bd
	s_mov_b32 s61, 0xf800000
	v_mov_b32_e32 v186, 0x260
	s_mov_b64 s[8:9], 0x16310000
	s_mov_b64 s[10:11], 0x21a10000
	s_mov_b64 s[12:13], 0x16320000
	s_mov_b64 s[14:15], 0x21a20000
	s_mov_b32 s16, 0x42000000
	s_mov_b32 s62, 0xc3e00000
	s_add_i32 s63, s20, 0
	v_mov_b32_e32 v187, 0x43e00000
	s_mov_b32 s66, s2
	s_branch .LBB0_1611
